# ssm2 scan: f32 input projection (16 v_pk_fma/step on VALU) moved to v_mfma_f32_32x32x2_f32 (exact f32, same k order) + v_permlane32_swap; recurrence unchanged
# speedup vs baseline: 1.0334x; 1.0082x over previous
; DI u32x4 pack8(const float* f) { u32x4 o; o.x = pack2(f[0], f[1]); o.y = pack2(f[2], f[3]); o.z = pack2(f[4], f[5]); o.w = pack2(f[6], f[7]); return o; }
; DI void ssm2_item(PREF p, int l, int item, unsigned char* ldsb) {
;     ...
;   const int hcol = lane & 15, q4 = lane >> 4;
;   bf16x8 cf[4];
;   {
;     const float* cre = p.c_re + ((size_t)(l * 16 + g) * 16 + hcol) * 64;
;     const float* cim = p.c_im + ((size_t)(l * 16 + g) * 16 + hcol) * 64;
; #pragma unroll
;     for (int ks = 0; ks < 4; ++ks) {
;       float v[8];
; #pragma unroll
;       for (int j = 0; j < 8; ++j) {
;         int k = 32 * ks + 8 * q4 + j;
;         v[j] = (k & 1) ? -cim[k >> 1] : cre[k >> 1];
;       }
;       union { bf16x8 v8; u32x4 u; } cv; cv.u = pack8(v); cf[ks] = cv.v8;
;     }
;   }
;   const float dch = p.ssm_d[l * 256 + g * 16 + hcol];
;   for (int sub = 0; sub < 4; ++sub) {
;     for (int tt = 0; tt < 16; ++tt) {
;       SSM_STEP(sub * 16 + tt)
.LBB0_303:
	v_and_b32_e32 v62, 15, v79
	v_lshlrev_b64 v[22:23], 12, v[22:23]
	v_lshrrev_b32_e32 v0, 2, v79
	v_lshl_or_b32 v22, v62, 8, v22
	v_and_b32_e32 v64, 12, v0
	v_lshl_add_u64 v[26:27], s[46:47], 0, v[22:23]
	v_lshlrev_b32_e32 v0, 2, v64
	v_lshl_add_u64 v[58:59], v[26:27], 0, v[0:1]
	global_load_dwordx4 v[70:73], v[58:59], off
	v_lshl_add_u64 v[24:25], s[44:45], 0, v[22:23]
	v_lshl_add_u64 v[54:55], v[24:25], 0, v[0:1]
	global_load_dwordx4 v[74:77], v[54:55], off
	global_load_dwordx4 v[82:85], v[54:55], off offset:64
	global_load_dwordx4 v[86:89], v[58:59], off offset:64
	global_load_dwordx4 v[90:93], v[54:55], off offset:128
	global_load_dwordx4 v[94:97], v[58:59], off offset:128
	global_load_dwordx4 v[98:101], v[54:55], off offset:192
	global_load_dwordx4 v[102:105], v[58:59], off offset:192
	s_movk_i32 s0, 0x1100
	v_mul_lo_u32 v66, v80, s0
	v_add_u32_e32 v56, s33, v66
	v_and_b32_e32 v68, 48, v79
	s_waitcnt vmcnt(10)
	v_mov_b32_e32 v63, v14
	v_mov_b32_e32 v14, v3
	s_mov_b32 s8, 0
	s_waitcnt vmcnt(7)
	v_xor_b32_e32 v0, 0x80000000, v70
	v_xor_b32_e32 v26, 0x80000000, v71
	v_xor_b32_e32 v27, 0x80000000, v72
	v_xor_b32_e32 v28, 0x80000000, v73
	s_waitcnt vmcnt(6)
	v_cvt_pk_bf16_f32 v23, v75, v26
	v_cvt_pk_bf16_f32 v24, v76, v27
	v_cvt_pk_bf16_f32 v25, v77, v28
	v_cvt_pk_bf16_f32 v22, v74, v0
	s_waitcnt vmcnt(4)
	v_xor_b32_e32 v0, 0x80000000, v86
	v_xor_b32_e32 v30, 0x80000000, v87
	v_xor_b32_e32 v31, 0x80000000, v88
	v_xor_b32_e32 v32, 0x80000000, v89
	v_cvt_pk_bf16_f32 v27, v83, v30
	v_cvt_pk_bf16_f32 v28, v84, v31
	v_cvt_pk_bf16_f32 v29, v85, v32
	v_cvt_pk_bf16_f32 v26, v82, v0
	s_waitcnt vmcnt(2)
	v_xor_b32_e32 v0, 0x80000000, v94
	v_xor_b32_e32 v34, 0x80000000, v95
	v_xor_b32_e32 v35, 0x80000000, v96
	v_xor_b32_e32 v36, 0x80000000, v97
	v_cvt_pk_bf16_f32 v31, v91, v34
	v_cvt_pk_bf16_f32 v32, v92, v35
	v_cvt_pk_bf16_f32 v33, v93, v36
	s_nop 0
	s_load_dwordx2 s[0:1], s[10:11], 0xa8
	v_cvt_pk_bf16_f32 v30, v90, v0
	s_waitcnt vmcnt(0)
	v_xor_b32_e32 v0, 0x80000000, v102
	v_lshlrev_b32_e32 v58, 4, v81
	v_xor_b32_e32 v54, 0x80000000, v103
	v_cvt_pk_bf16_f32 v34, v98, v0
	v_add_u32_e32 v0, s56, v58
	v_xor_b32_e32 v55, 0x80000000, v104
	v_cvt_pk_bf16_f32 v35, v99, v54
	v_or_b32_e32 v54, v0, v62
	v_cvt_pk_bf16_f32 v36, v100, v55
	v_ashrrev_i32_e32 v55, 31, v54
	s_waitcnt lgkmcnt(0)
	v_lshl_add_u64 v[54:55], v[54:55], 2, s[0:1]
	global_load_dword v65, v[54:55], off
	v_xor_b32_e32 v57, 0x80000000, v105
	s_movk_i32 s0, 0xef40
	v_mad_u64_u32 v[54:55], s[0:1], v80, s0, v[56:57]
	s_movk_i32 s0, 0x110
	s_nop 0
	v_mad_u32_u24 v67, v62, s0, v56
	s_load_dwordx2 s[0:1], s[10:11], 0x178
	v_ashrrev_i32_e32 v59, 31, v58
	v_cvt_pk_bf16_f32 v37, v101, v57
	v_lshlrev_b32_e32 v0, 1, v62
	v_mov_b32_e32 v60, v46
	s_waitcnt lgkmcnt(0)
	v_lshl_add_u64 v[56:57], v[58:59], 1, s[0:1]
	v_mov_b32_e32 v58, v5
	v_mov_b32_e32 v5, v16
	v_mov_b32_e32 v16, v38
	v_lshl_or_b32 v38, v78, 2, v66
	v_readlane_b32 s0, v254, 24
	v_lshl_add_u64 v[56:57], v[56:57], 0, v[0:1]
	v_lshl_add_u32 v0, v62, 2, v54
	v_mov_b32_e32 v59, v17
	v_mov_b32_e32 v61, v10
	v_mov_b32_e32 v10, v47
	v_mov_b32_e32 v46, v48
	v_mov_b32_e32 v47, v12
	v_mov_b32_e32 v12, v49
	v_mov_b32_e32 v48, v42
	v_mov_b32_e32 v49, v6
	v_mov_b32_e32 v6, v43
	v_mov_b32_e32 v42, v44
	v_mov_b32_e32 v43, v8
	v_mov_b32_e32 v8, v45
	v_mov_b32_e32 v17, v18
	v_mov_b32_e32 v18, v39
	v_mov_b32_e32 v44, v40
	v_mov_b32_e32 v45, v20
	v_mov_b32_e32 v20, v41
	v_mov_b32_e32 v62, v2
	v_pk_mov_b32 v[2:3], v[50:51], v[50:51] op_sel:[1,0]
	v_add_u32_e32 v55, s0, v38
	v_add_u32_e32 v66, v67, v68
	s_waitcnt vmcnt(0)
	v_permlane32_swap_b32 v16, v18
	v_permlane32_swap_b32 v17, v19
	v_permlane32_swap_b32 v44, v20
	v_permlane32_swap_b32 v45, v21
	v_permlane32_swap_b32 v62, v14
	v_permlane32_swap_b32 v63, v15
	v_permlane32_swap_b32 v4, v58
	v_permlane32_swap_b32 v5, v59
	v_permlane32_swap_b32 v60, v10
	v_permlane32_swap_b32 v61, v11
	v_permlane32_swap_b32 v46, v12
	v_permlane32_swap_b32 v47, v13
	v_permlane32_swap_b32 v48, v6
	v_permlane32_swap_b32 v49, v7
	v_permlane32_swap_b32 v42, v8
	v_permlane32_swap_b32 v43, v9
	v_bfe_u32 v128, v172, 2, 1
	v_bfe_u32 v129, v172, 3, 2
	v_and_b32_e32 v130, 3, v172
	v_lshlrev_b32_e32 v128, 4, v128
	v_lshl_add_u32 v128, v129, 2, v128
	v_add_u32_e32 v128, v128, v130
	v_lshlrev_b32_e32 v128, 8, v128
	v_lshrrev_b32_e32 v129, 5, v172
	v_lshl_add_u32 v126, v129, 2, v128
; DI unsigned pack2(float a, float b) { unsigned r; asm("v_cvt_pk_bf16_f32 %0, %1, %2\n\ts_nop 1" : "=v"(r) : "v"(a), "v"(b)); return r; }
; DI void ssm2_item(PREF p, int l, int item, unsigned char* ldsb) {
;     ...
;   for (int sub = 0; sub < 4; ++sub) {
;     for (int tt = 0; tt < 16; ++tt) {
;       SSM_STEP(sub * 16 + tt)
;       *(unsigned*)(Hs + tt * 136 + 2 * lane) = pack2(hr, hi);
.LBB0_304:
	v_mov_b32_e32 v38, v55
	s_mov_b32 s9, 0
	s_and_b32 s98, s8, 1
	s_cmp_lg_u32 s98, 0
	s_cbranch_scc1 .Lmy_ssm2_odd
	v_add_u32_e32 v127, v54, v126
	ds_read2_b32 v[118:119], v127 offset0:0 offset1:2
	ds_read2_b32 v[120:121], v127 offset0:4 offset1:6
	ds_read2_b32 v[122:123], v127 offset0:8 offset1:10
	ds_read2_b32 v[124:125], v127 offset0:12 offset1:14
	s_waitcnt lgkmcnt(0)
	v_mfma_f32_32x32x2_f32 v[184:199], v118, v16, 0
	v_mfma_f32_32x32x2_f32 v[200:215], v118, v17, 0
	v_mfma_f32_32x32x2_f32 v[216:231], v118, v18, 0
	v_mfma_f32_32x32x2_f32 v[232:247], v118, v19, 0
	v_mfma_f32_32x32x2_f32 v[184:199], v119, v44, v[184:199]
	v_mfma_f32_32x32x2_f32 v[200:215], v119, v45, v[200:215]
	v_mfma_f32_32x32x2_f32 v[216:231], v119, v20, v[216:231]
	v_mfma_f32_32x32x2_f32 v[232:247], v119, v21, v[232:247]
	v_mfma_f32_32x32x2_f32 v[184:199], v120, v62, v[184:199]
	v_mfma_f32_32x32x2_f32 v[200:215], v120, v63, v[200:215]
	v_mfma_f32_32x32x2_f32 v[216:231], v120, v14, v[216:231]
	v_mfma_f32_32x32x2_f32 v[232:247], v120, v15, v[232:247]
	v_mfma_f32_32x32x2_f32 v[184:199], v121, v4, v[184:199]
	v_mfma_f32_32x32x2_f32 v[200:215], v121, v5, v[200:215]
	v_mfma_f32_32x32x2_f32 v[216:231], v121, v58, v[216:231]
	v_mfma_f32_32x32x2_f32 v[232:247], v121, v59, v[232:247]
	v_mfma_f32_32x32x2_f32 v[184:199], v122, v60, v[184:199]
	v_mfma_f32_32x32x2_f32 v[200:215], v122, v61, v[200:215]
	v_mfma_f32_32x32x2_f32 v[216:231], v122, v10, v[216:231]
	v_mfma_f32_32x32x2_f32 v[232:247], v122, v11, v[232:247]
	v_mfma_f32_32x32x2_f32 v[184:199], v123, v46, v[184:199]
	v_mfma_f32_32x32x2_f32 v[200:215], v123, v47, v[200:215]
	v_mfma_f32_32x32x2_f32 v[216:231], v123, v12, v[216:231]
	v_mfma_f32_32x32x2_f32 v[232:247], v123, v13, v[232:247]
	v_mfma_f32_32x32x2_f32 v[184:199], v124, v48, v[184:199]
	v_mfma_f32_32x32x2_f32 v[200:215], v124, v49, v[200:215]
	v_mfma_f32_32x32x2_f32 v[216:231], v124, v6, v[216:231]
	v_mfma_f32_32x32x2_f32 v[232:247], v124, v7, v[232:247]
	v_mfma_f32_32x32x2_f32 v[184:199], v125, v42, v[184:199]
	v_mfma_f32_32x32x2_f32 v[200:215], v125, v43, v[200:215]
	v_mfma_f32_32x32x2_f32 v[216:231], v125, v8, v[216:231]
	v_mfma_f32_32x32x2_f32 v[232:247], v125, v9, v[232:247]
	s_nop 18
	v_permlane32_swap_b32 v184, v216
	s_nop 18
	v_permlane32_swap_b32 v200, v232
	s_nop 16
	v_permlane32_swap_b32 v185, v217
	s_nop 16
	v_permlane32_swap_b32 v201, v233
	s_nop 14
	v_permlane32_swap_b32 v186, v218
	s_nop 14
	v_permlane32_swap_b32 v202, v234
	s_nop 12
	v_permlane32_swap_b32 v187, v219
	s_nop 12
	v_permlane32_swap_b32 v203, v235
	s_nop 10
	v_permlane32_swap_b32 v188, v220
	s_nop 10
	v_permlane32_swap_b32 v204, v236
	s_nop 8
	v_permlane32_swap_b32 v189, v221
	s_nop 8
	v_permlane32_swap_b32 v205, v237
	s_nop 6
	v_permlane32_swap_b32 v190, v222
	s_nop 6
	v_permlane32_swap_b32 v206, v238
	s_nop 4
	v_permlane32_swap_b32 v191, v223
	s_nop 4
	v_permlane32_swap_b32 v207, v239
	s_nop 2
	v_permlane32_swap_b32 v192, v224
	s_nop 2
	v_permlane32_swap_b32 v208, v240
	s_nop 0
	v_permlane32_swap_b32 v193, v225
	s_nop 0
	v_permlane32_swap_b32 v209, v241
	v_permlane32_swap_b32 v194, v226
	v_permlane32_swap_b32 v210, v242
	v_permlane32_swap_b32 v195, v227
	v_permlane32_swap_b32 v211, v243
	v_permlane32_swap_b32 v196, v228
	v_permlane32_swap_b32 v212, v244
	v_permlane32_swap_b32 v197, v229
	v_permlane32_swap_b32 v213, v245
	v_permlane32_swap_b32 v198, v230
	v_permlane32_swap_b32 v214, v246
	v_permlane32_swap_b32 v199, v231
	v_permlane32_swap_b32 v215, v247
	v_mul_f32_e32 v128, v51, v53
	v_mul_f32_e32 v129, v50, v53
	v_fma_f32 v130, v50, v52, -v128
	v_fma_f32 v131, v51, v52, v129
	v_add_f32_e32 v40, v130, v184
	v_add_f32_e32 v41, v131, v200
	v_cvt_pk_bf16_f32 v132, v40, v41
	ds_write_b32 v38, v132 offset:0
	v_mul_f32_e32 v128, v51, v41
	v_mul_f32_e32 v129, v50, v41
	v_fma_f32 v130, v50, v40, -v128
	v_fma_f32 v131, v51, v40, v129
	v_add_f32_e32 v52, v130, v185
	v_add_f32_e32 v53, v131, v201
	v_cvt_pk_bf16_f32 v133, v52, v53
	ds_write_b32 v38, v133 offset:272
	v_mul_f32_e32 v128, v51, v53
	v_mul_f32_e32 v129, v50, v53
	v_fma_f32 v130, v50, v52, -v128
	v_fma_f32 v131, v51, v52, v129
	v_add_f32_e32 v40, v130, v186
	v_add_f32_e32 v41, v131, v202
	v_cvt_pk_bf16_f32 v132, v40, v41
	ds_write_b32 v38, v132 offset:544
	v_mul_f32_e32 v128, v51, v41
	v_mul_f32_e32 v129, v50, v41
	v_fma_f32 v130, v50, v40, -v128
	v_fma_f32 v131, v51, v40, v129
	v_add_f32_e32 v52, v130, v187
	v_add_f32_e32 v53, v131, v203
	v_cvt_pk_bf16_f32 v133, v52, v53
	ds_write_b32 v38, v133 offset:816
	v_mul_f32_e32 v128, v51, v53
	v_mul_f32_e32 v129, v50, v53
	v_fma_f32 v130, v50, v52, -v128
	v_fma_f32 v131, v51, v52, v129
	v_add_f32_e32 v40, v130, v188
	v_add_f32_e32 v41, v131, v204
	v_cvt_pk_bf16_f32 v132, v40, v41
	ds_write_b32 v38, v132 offset:1088
	v_mul_f32_e32 v128, v51, v41
	v_mul_f32_e32 v129, v50, v41
	v_fma_f32 v130, v50, v40, -v128
	v_fma_f32 v131, v51, v40, v129
	v_add_f32_e32 v52, v130, v189
	v_add_f32_e32 v53, v131, v205
	v_cvt_pk_bf16_f32 v133, v52, v53
	ds_write_b32 v38, v133 offset:1360
	v_mul_f32_e32 v128, v51, v53
	v_mul_f32_e32 v129, v50, v53
	v_fma_f32 v130, v50, v52, -v128
	v_fma_f32 v131, v51, v52, v129
	v_add_f32_e32 v40, v130, v190
	v_add_f32_e32 v41, v131, v206
	v_cvt_pk_bf16_f32 v132, v40, v41
	ds_write_b32 v38, v132 offset:1632
	v_mul_f32_e32 v128, v51, v41
	v_mul_f32_e32 v129, v50, v41
	v_fma_f32 v130, v50, v40, -v128
	v_fma_f32 v131, v51, v40, v129
	v_add_f32_e32 v52, v130, v191
	v_add_f32_e32 v53, v131, v207
	v_cvt_pk_bf16_f32 v133, v52, v53
	ds_write_b32 v38, v133 offset:1904
	v_mul_f32_e32 v128, v51, v53
	v_mul_f32_e32 v129, v50, v53
	v_fma_f32 v130, v50, v52, -v128
	v_fma_f32 v131, v51, v52, v129
; DI unsigned pack2(float a, float b) { unsigned r; asm("v_cvt_pk_bf16_f32 %0, %1, %2\n\ts_nop 1" : "=v"(r) : "v"(a), "v"(b)); return r; }
; DI void ssm2_item(PREF p, int l, int item, unsigned char* ldsb) {
;     ...
;   for (int sub = 0; sub < 4; ++sub) {
;     for (int tt = 0; tt < 16; ++tt) {
;       SSM_STEP(sub * 16 + tt)
;       *(unsigned*)(Hs + tt * 136 + 2 * lane) = pack2(hr, hi);
	v_add_f32_e32 v40, v130, v192
	v_add_f32_e32 v41, v131, v208
	v_cvt_pk_bf16_f32 v132, v40, v41
	ds_write_b32 v38, v132 offset:2176
	v_mul_f32_e32 v128, v51, v41
	v_mul_f32_e32 v129, v50, v41
	v_fma_f32 v130, v50, v40, -v128
	v_fma_f32 v131, v51, v40, v129
	v_add_f32_e32 v52, v130, v193
	v_add_f32_e32 v53, v131, v209
	v_cvt_pk_bf16_f32 v133, v52, v53
	ds_write_b32 v38, v133 offset:2448
	v_mul_f32_e32 v128, v51, v53
	v_mul_f32_e32 v129, v50, v53
	v_fma_f32 v130, v50, v52, -v128
	v_fma_f32 v131, v51, v52, v129
	v_add_f32_e32 v40, v130, v194
	v_add_f32_e32 v41, v131, v210
	v_cvt_pk_bf16_f32 v132, v40, v41
	ds_write_b32 v38, v132 offset:2720
	v_mul_f32_e32 v128, v51, v41
	v_mul_f32_e32 v129, v50, v41
	v_fma_f32 v130, v50, v40, -v128
	v_fma_f32 v131, v51, v40, v129
	v_add_f32_e32 v52, v130, v195
	v_add_f32_e32 v53, v131, v211
	v_cvt_pk_bf16_f32 v133, v52, v53
	ds_write_b32 v38, v133 offset:2992
	v_mul_f32_e32 v128, v51, v53
	v_mul_f32_e32 v129, v50, v53
	v_fma_f32 v130, v50, v52, -v128
	v_fma_f32 v131, v51, v52, v129
	v_add_f32_e32 v40, v130, v196
	v_add_f32_e32 v41, v131, v212
	v_cvt_pk_bf16_f32 v132, v40, v41
	ds_write_b32 v38, v132 offset:3264
	v_mul_f32_e32 v128, v51, v41
	v_mul_f32_e32 v129, v50, v41
	v_fma_f32 v130, v50, v40, -v128
	v_fma_f32 v131, v51, v40, v129
	v_add_f32_e32 v52, v130, v197
	v_add_f32_e32 v53, v131, v213
	v_cvt_pk_bf16_f32 v133, v52, v53
	ds_write_b32 v38, v133 offset:3536
	v_mul_f32_e32 v128, v51, v53
	v_mul_f32_e32 v129, v50, v53
	v_fma_f32 v130, v50, v52, -v128
	v_fma_f32 v131, v51, v52, v129
	v_add_f32_e32 v40, v130, v198
	v_add_f32_e32 v41, v131, v214
	v_cvt_pk_bf16_f32 v132, v40, v41
	ds_write_b32 v38, v132 offset:3808
	v_mul_f32_e32 v128, v51, v41
	v_mul_f32_e32 v129, v50, v41
	v_fma_f32 v130, v50, v40, -v128
	v_fma_f32 v131, v51, v40, v129
	v_add_f32_e32 v52, v130, v199
	v_add_f32_e32 v53, v131, v215
	v_cvt_pk_bf16_f32 v133, v52, v53
	ds_write_b32 v38, v133 offset:4080
	s_branch .Lmy_ssm2_done
.Lmy_ssm2_odd:
	v_mul_f32_e32 v128, v51, v53
	v_mul_f32_e32 v129, v50, v53
	v_fma_f32 v130, v50, v52, -v128
	v_fma_f32 v131, v51, v52, v129
	v_add_f32_e32 v40, v130, v216
	v_add_f32_e32 v41, v131, v232
	v_cvt_pk_bf16_f32 v132, v40, v41
	ds_write_b32 v38, v132 offset:0
	v_mul_f32_e32 v128, v51, v41
	v_mul_f32_e32 v129, v50, v41
	v_fma_f32 v130, v50, v40, -v128
	v_fma_f32 v131, v51, v40, v129
	v_add_f32_e32 v52, v130, v217
	v_add_f32_e32 v53, v131, v233
	v_cvt_pk_bf16_f32 v133, v52, v53
	ds_write_b32 v38, v133 offset:272
	v_mul_f32_e32 v128, v51, v53
	v_mul_f32_e32 v129, v50, v53
	v_fma_f32 v130, v50, v52, -v128
	v_fma_f32 v131, v51, v52, v129
	v_add_f32_e32 v40, v130, v218
	v_add_f32_e32 v41, v131, v234
	v_cvt_pk_bf16_f32 v132, v40, v41
	ds_write_b32 v38, v132 offset:544
	v_mul_f32_e32 v128, v51, v41
	v_mul_f32_e32 v129, v50, v41
	v_fma_f32 v130, v50, v40, -v128
	v_fma_f32 v131, v51, v40, v129
	v_add_f32_e32 v52, v130, v219
	v_add_f32_e32 v53, v131, v235
	v_cvt_pk_bf16_f32 v133, v52, v53
	ds_write_b32 v38, v133 offset:816
	v_mul_f32_e32 v128, v51, v53
	v_mul_f32_e32 v129, v50, v53
	v_fma_f32 v130, v50, v52, -v128
	v_fma_f32 v131, v51, v52, v129
	v_add_f32_e32 v40, v130, v220
	v_add_f32_e32 v41, v131, v236
	v_cvt_pk_bf16_f32 v132, v40, v41
	ds_write_b32 v38, v132 offset:1088
	v_mul_f32_e32 v128, v51, v41
	v_mul_f32_e32 v129, v50, v41
	v_fma_f32 v130, v50, v40, -v128
	v_fma_f32 v131, v51, v40, v129
	v_add_f32_e32 v52, v130, v221
	v_add_f32_e32 v53, v131, v237
	v_cvt_pk_bf16_f32 v133, v52, v53
	ds_write_b32 v38, v133 offset:1360
	v_mul_f32_e32 v128, v51, v53
	v_mul_f32_e32 v129, v50, v53
	v_fma_f32 v130, v50, v52, -v128
	v_fma_f32 v131, v51, v52, v129
	v_add_f32_e32 v40, v130, v222
	v_add_f32_e32 v41, v131, v238
	v_cvt_pk_bf16_f32 v132, v40, v41
	ds_write_b32 v38, v132 offset:1632
	v_mul_f32_e32 v128, v51, v41
	v_mul_f32_e32 v129, v50, v41
	v_fma_f32 v130, v50, v40, -v128
	v_fma_f32 v131, v51, v40, v129
	v_add_f32_e32 v52, v130, v223
	v_add_f32_e32 v53, v131, v239
	v_cvt_pk_bf16_f32 v133, v52, v53
	ds_write_b32 v38, v133 offset:1904
	v_mul_f32_e32 v128, v51, v53
	v_mul_f32_e32 v129, v50, v53
	v_fma_f32 v130, v50, v52, -v128
	v_fma_f32 v131, v51, v52, v129
	v_add_f32_e32 v40, v130, v224
	v_add_f32_e32 v41, v131, v240
	v_cvt_pk_bf16_f32 v132, v40, v41
	ds_write_b32 v38, v132 offset:2176
	v_mul_f32_e32 v128, v51, v41
	v_mul_f32_e32 v129, v50, v41
	v_fma_f32 v130, v50, v40, -v128
	v_fma_f32 v131, v51, v40, v129
	v_add_f32_e32 v52, v130, v225
	v_add_f32_e32 v53, v131, v241
	v_cvt_pk_bf16_f32 v133, v52, v53
	ds_write_b32 v38, v133 offset:2448
	v_mul_f32_e32 v128, v51, v53
	v_mul_f32_e32 v129, v50, v53
	v_fma_f32 v130, v50, v52, -v128
	v_fma_f32 v131, v51, v52, v129
	v_add_f32_e32 v40, v130, v226
	v_add_f32_e32 v41, v131, v242
	v_cvt_pk_bf16_f32 v132, v40, v41
	ds_write_b32 v38, v132 offset:2720
	v_mul_f32_e32 v128, v51, v41
	v_mul_f32_e32 v129, v50, v41
	v_fma_f32 v130, v50, v40, -v128
	v_fma_f32 v131, v51, v40, v129
	v_add_f32_e32 v52, v130, v227
	v_add_f32_e32 v53, v131, v243
	v_cvt_pk_bf16_f32 v133, v52, v53
	ds_write_b32 v38, v133 offset:2992
	v_mul_f32_e32 v128, v51, v53
	v_mul_f32_e32 v129, v50, v53
	v_fma_f32 v130, v50, v52, -v128
	v_fma_f32 v131, v51, v52, v129
	v_add_f32_e32 v40, v130, v228
	v_add_f32_e32 v41, v131, v244
	v_cvt_pk_bf16_f32 v132, v40, v41
	ds_write_b32 v38, v132 offset:3264
	v_mul_f32_e32 v128, v51, v41
	v_mul_f32_e32 v129, v50, v41
	v_fma_f32 v130, v50, v40, -v128
	v_fma_f32 v131, v51, v40, v129
	v_add_f32_e32 v52, v130, v229
	v_add_f32_e32 v53, v131, v245
	v_cvt_pk_bf16_f32 v133, v52, v53
	ds_write_b32 v38, v133 offset:3536
	v_mul_f32_e32 v128, v51, v53
	v_mul_f32_e32 v129, v50, v53
	v_fma_f32 v130, v50, v52, -v128
	v_fma_f32 v131, v51, v52, v129
	v_add_f32_e32 v40, v130, v230
	v_add_f32_e32 v41, v131, v246
	v_cvt_pk_bf16_f32 v132, v40, v41
	ds_write_b32 v38, v132 offset:3808
	v_mul_f32_e32 v128, v51, v41
	v_mul_f32_e32 v129, v50, v41
	v_fma_f32 v130, v50, v40, -v128
	v_fma_f32 v131, v51, v40, v129
	v_add_f32_e32 v52, v130, v231
	v_add_f32_e32 v53, v131, v247
	v_cvt_pk_bf16_f32 v133, v52, v53
	ds_write_b32 v38, v133 offset:4080
; DI u16 f2bf(float x) { return (u16)(pack2(x, x) & 0xffffu); }
; DI float gelu_t(float x) { float u = 0.7978845608028654f * (x + 0.044715f * x * x * x); return x / (1.f + __expf(-2.f * u)); }
; #define MFMA16(a, b, c) __builtin_amdgcn_mfma_f32_16x16x32_bf16((a), (b), (c), 0, 0, 0)
; DI void ssm2_item(PREF p, int l, int item, unsigned char* ldsb) {
;     ...
;     __syncthreads();
;     f32x4 acc = {0.f, 0.f, 0.f, 0.f};
; #pragma unroll
;     for (int ks = 0; ks < 4; ++ks) {
;       bf16x8 a = *(const bf16x8*)(Hs + hcol * 136 + 32 * ks + 8 * q4);
;       acc = MFMA16(a, cf[ks], acc);
;     }
; #pragma unroll
;     for (int j = 0; j < 4; ++j) {
;       int t = sub * 16 + 4 * q4 + j;
;       float uu = uS[t * 64 + w * 16 + hcol];
;       float yv = gelu_t(acc[j] + dch * uu);
;       p.yss[(size_t)(b * S_ + c * 64 + t) * 256 + g * 16 + hcol] = f2bf(yv);
;     }
;     __syncthreads();
;   }
.Lmy_ssm2_done:
	s_waitcnt lgkmcnt(0)
	s_barrier
	ds_read_b128 v[38:41], v66 offset:16384
	ds_read_b128 v[68:71], v66 offset:16448
	v_lshl_or_b32 v67, s8, 4, v64
	s_add_i32 s8, s8, 1
	v_add_u32_e32 v54, 0x1000, v54
	s_cmp_eq_u32 s8, 4
	s_waitcnt lgkmcnt(1)
	v_mfma_f32_16x16x32_bf16 v[38:41], v[38:41], v[22:25], 0
	s_waitcnt lgkmcnt(0)
	v_mfma_f32_16x16x32_bf16 v[38:41], v[68:71], v[26:29], v[38:41]
	ds_read_b128 v[68:71], v66 offset:16512
	s_waitcnt lgkmcnt(0)
	v_mfma_f32_16x16x32_bf16 v[38:41], v[68:71], v[30:33], v[38:41]
	ds_read_b128 v[68:71], v66 offset:16576
	s_waitcnt lgkmcnt(0)
	v_mfma_f32_16x16x32_bf16 v[38:41], v[68:71], v[34:37], v[38:41]
	v_lshl_add_u32 v68, v67, 8, v0
	ds_read_b32 v68, v68
	s_waitcnt lgkmcnt(0)
	s_nop 4
	v_fma_f32 v38, v65, v68, v38
	v_mul_f32_e32 v68, 0x3d372713, v38
	v_mul_f32_e32 v68, v38, v68
	v_fma_f32 v68, v38, v68, v38
	v_mul_f32_e32 v68, 0x3f4c422a, v68
	v_mul_f32_e32 v68, -2.0, v68
	v_mul_f32_e32 v68, 0x3fb8aa3b, v68
	v_exp_f32_e32 v68, v68
	s_nop 0
	v_add_f32_e32 v68, 1.0, v68
	v_rcp_f32_e32 v69, v68
	s_nop 0
	v_mul_f32_e32 v38, v38, v69
	v_or_b32_e32 v68, s62, v67
	v_ashrrev_i32_e32 v69, 31, v68
	v_lshlrev_b64 v[68:69], 9, v[68:69]
	v_cvt_pk_bf16_f32 v38, v38, v38
	v_lshl_add_u64 v[68:69], v[56:57], 0, v[68:69]
	global_store_short v[68:69], v38, off
	v_or_b32_e32 v38, 1, v67
	v_lshl_add_u32 v68, v38, 8, v0
	ds_read_b32 v68, v68
	v_or_b32_e32 v38, s62, v38
	s_waitcnt lgkmcnt(0)
	v_fma_f32 v39, v65, v68, v39
	v_mul_f32_e32 v68, 0x3d372713, v39
	v_mul_f32_e32 v68, v39, v68
	v_fma_f32 v68, v39, v68, v39
	v_mul_f32_e32 v68, 0x3f4c422a, v68
	v_mul_f32_e32 v68, -2.0, v68
	v_mul_f32_e32 v68, 0x3fb8aa3b, v68
	v_exp_f32_e32 v68, v68
	s_nop 0
	v_add_f32_e32 v68, 1.0, v68
	v_rcp_f32_e32 v69, v68
	s_nop 0
	v_mul_f32_e32 v39, v39, v69
	v_cvt_pk_bf16_f32 v68, v39, v39
	v_ashrrev_i32_e32 v39, 31, v38
	v_lshlrev_b64 v[38:39], 9, v[38:39]
	v_lshl_add_u64 v[38:39], v[56:57], 0, v[38:39]
	global_store_short v[38:39], v68, off
	v_or_b32_e32 v38, 2, v67
	v_lshl_add_u32 v39, v38, 8, v0
	ds_read_b32 v39, v39
	v_or_b32_e32 v38, s62, v38
	s_waitcnt lgkmcnt(0)
	v_fma_f32 v39, v65, v39, v40
	v_mul_f32_e32 v40, 0x3d372713, v39
	v_mul_f32_e32 v40, v39, v40
	v_fma_f32 v40, v39, v40, v39
	v_mul_f32_e32 v40, 0x3f4c422a, v40
	v_mul_f32_e32 v40, -2.0, v40
	v_mul_f32_e32 v40, 0x3fb8aa3b, v40
	v_exp_f32_e32 v40, v40
	s_nop 0
	v_add_f32_e32 v40, 1.0, v40
	v_rcp_f32_e32 v68, v40
	s_nop 0
	v_mul_f32_e32 v39, v39, v68
	v_cvt_pk_bf16_f32 v40, v39, v39
	v_ashrrev_i32_e32 v39, 31, v38
	v_lshlrev_b64 v[38:39], 9, v[38:39]
	v_lshl_add_u64 v[38:39], v[56:57], 0, v[38:39]
	global_store_short v[38:39], v40, off
	v_or_b32_e32 v38, 3, v67
	v_lshl_add_u32 v39, v38, 8, v0
	ds_read_b32 v39, v39
	v_or_b32_e32 v38, s62, v38
	s_waitcnt lgkmcnt(0)
	v_fmac_f32_e32 v41, v65, v39
	v_mul_f32_e32 v39, 0x3d372713, v41
	v_mul_f32_e32 v39, v41, v39
	v_fma_f32 v39, v41, v39, v41
	v_mul_f32_e32 v39, 0x3f4c422a, v39
	v_mul_f32_e32 v39, -2.0, v39
	v_mul_f32_e32 v39, 0x3fb8aa3b, v39
	v_exp_f32_e32 v39, v39
	s_nop 0
	v_add_f32_e32 v39, 1.0, v39
	v_rcp_f32_e32 v40, v39
	s_nop 0
	v_mul_f32_e32 v39, v41, v40
	v_cvt_pk_bf16_f32 v40, v39, v39
	v_ashrrev_i32_e32 v39, 31, v38
	v_lshlrev_b64 v[38:39], 9, v[38:39]
	v_lshl_add_u64 v[38:39], v[56:57], 0, v[38:39]
	global_store_short v[38:39], v40, off
	s_barrier
	s_cbranch_scc0 .LBB0_304
	s_add_i32 s48, s48, s71
	s_sub_i32 s57, s57, s71
	s_cmpk_gt_i32 s48, 0x7ff
	s_cbranch_scc0 .LBB0_268
